# P0: w_out transposes moved to the waves that have 8 rows (balance)
# baseline (speedup 1.0000x reference)
.LBB0_8:
	s_add_i32 s2, s8, 0x200
	s_cmpk_lt_i32 s8, 0x600
	s_cbranch_scc1 .LBB0_13
	s_cmpk_gt_i32 s8, 0x7ff
	s_mov_b32 s8, s2
	s_cbranch_scc1 .LBB0_13

.Lpost_getpc1:
	s_add_u32 s98, s98, (.LBB0_930-.Lpost_getpc1)&4294967295
	s_addc_u32 s99, s99, (.LBB0_930-.Lpost_getpc1)>>32
	s_setpc_b64 s[98:99]
	s_nop 0
	s_nop 0
	s_nop 0
	s_nop 0
	s_nop 0
	s_nop 0
	s_nop 0
	s_nop 0
	s_nop 0
	s_nop 0
	s_nop 0
	s_nop 0
	s_nop 0
	s_nop 0
	s_nop 0
	s_nop 0
	s_nop 0
	s_nop 0
	s_nop 0
	s_nop 0
	s_nop 0
	s_nop 0
	s_nop 0
	s_nop 0
	s_nop 0
	s_nop 0
	s_nop 0
	s_nop 0
	s_nop 0
	s_nop 0
	s_nop 0
	s_nop 0
	s_nop 0
	s_nop 0
	s_nop 0
	s_nop 0
	s_nop 0
	s_nop 0
	s_nop 0
	s_nop 0
	s_nop 0
	s_nop 0
	s_nop 0
	s_nop 0
	s_nop 0
	s_nop 0
	s_nop 0
	s_nop 0
	s_nop 0
	s_nop 0
	s_nop 0
	s_nop 0
	s_nop 0
	s_nop 0
	s_nop 0
	s_nop 0
	s_nop 0
	s_nop 0
	s_nop 0
	s_nop 0
.LBB0_124:
	v_mov_b32_e32 v14, v0
	s_cmp_gt_i32 s95, -1
	v_readfirstlane_b32 s2, v14
	s_cbranch_scc0 .LBB0_126
	s_lshl_b32 s4, s95, 7
	s_cbranch_execz .LBB0_127
	s_branch .LBB0_128
